# attention non-masked loop: v_mov copies coalesced into the producing v_exp (11 of 32 per iteration)
# baseline (speedup 1.0000x reference)
.Lattn_nm:
	v_add_u32_e32 v66, 0x2000, v213
	ds_read_b128 v[152:155], v212
	ds_read_b128 v[156:159], v212 offset:32
	ds_read_b128 v[160:163], v212 offset:64
	ds_read_b128 v[224:227], v212 offset:96
	ds_read2_b64 v[114:117], v213 offset1:2
	ds_read2_b64 v[118:121], v213 offset0:4 offset1:6
	ds_read2_b64 v[126:129], v66 offset0:64 offset1:66
	ds_read2_b64 v[122:125], v66 offset0:68 offset1:70
	s_waitcnt vmcnt(7) lgkmcnt(7)
	v_mfma_f32_32x32x16_bf16 v[66:81], v[152:155], v[82:85], 0
	v_add_u32_e32 v223, s11, v203
	s_add_i32 s11, s11, 32
	v_add_u32_e32 v213, 64, v213
	v_add_u32_e32 v212, 0x1200, v212
	s_cmpk_lg_i32 s11, 0x80
	s_waitcnt vmcnt(6) lgkmcnt(6)
	v_mfma_f32_32x32x16_bf16 v[66:81], v[156:159], v[86:89], v[66:81]
	s_waitcnt vmcnt(5) lgkmcnt(5)
	v_mfma_f32_32x32x16_bf16 v[66:81], v[160:163], v[90:93], v[66:81]
	s_waitcnt vmcnt(4) lgkmcnt(4)
	v_mfma_f32_32x32x16_bf16 v[66:81], v[224:227], v[94:97], v[66:81]
	s_nop 11
	v_mul_f32_e32 v66, 0x3fb8aa3b, v66
	v_exp_f32_e32 v148, v66
	v_mul_f32_e32 v66, 0x3fb8aa3b, v67
	v_exp_f32_e32 v180, v66
	v_mul_f32_e32 v66, 0x3fb8aa3b, v68
	v_exp_f32_e32 v181, v66
	v_mul_f32_e32 v66, 0x3fb8aa3b, v69
	v_exp_f32_e32 v182, v66
	v_mul_f32_e32 v66, 0x3fb8aa3b, v70
	v_exp_f32_e32 v183, v66
	v_mul_f32_e32 v66, 0x3fb8aa3b, v71
	v_exp_f32_e32 v184, v66
	v_mul_f32_e32 v66, 0x3fb8aa3b, v72
	v_exp_f32_e32 v149, v66
	v_mul_f32_e32 v66, 0x3fb8aa3b, v73
	v_exp_f32_e32 v222, v66
	v_mul_f32_e32 v66, 0x3fb8aa3b, v74
	v_exp_f32_e32 v221, v66
	v_mul_f32_e32 v66, 0x3fb8aa3b, v75
	v_exp_f32_e32 v220, v66
	v_mul_f32_e32 v66, 0x3fb8aa3b, v76
	v_exp_f32_e32 v219, v66
	v_mul_f32_e32 v66, 0x3fb8aa3b, v77
	v_exp_f32_e32 v218, v66
	v_mul_f32_e32 v66, 0x3fb8aa3b, v78
	v_exp_f32_e32 v217, v66
	v_mul_f32_e32 v66, 0x3fb8aa3b, v79
	v_exp_f32_e32 v216, v66
	v_mul_f32_e32 v66, 0x3fb8aa3b, v80
	v_exp_f32_e32 v215, v66
	v_mul_f32_e32 v66, 0x3fb8aa3b, v81
	v_exp_f32_e32 v214, v66
	s_waitcnt vmcnt(3)
	v_mfma_f32_32x32x16_bf16 v[66:81], v[152:155], v[98:101], 0
	s_waitcnt vmcnt(2)
	v_mfma_f32_32x32x16_bf16 v[66:81], v[156:159], v[102:105], v[66:81]
	s_waitcnt vmcnt(1)
	v_mfma_f32_32x32x16_bf16 v[66:81], v[160:163], v[106:109], v[66:81]
	s_waitcnt vmcnt(0)
	v_mfma_f32_32x32x16_bf16 v[66:81], v[224:227], v[110:113], v[66:81]
	s_nop 9
	s_nop 1
	v_mul_f32_e32 v70, 0x3fb8aa3b, v70
	v_exp_f32_e32 v159, v70
	v_mul_f32_e32 v70, 0x3fb8aa3b, v71
	v_mul_f32_e32 v66, 0x3fb8aa3b, v66
	v_exp_f32_e32 v161, v70
	v_exp_f32_e32 v66, v66
	v_mul_f32_e32 v67, 0x3fb8aa3b, v67
	v_exp_f32_e32 v153, v67
	v_mov_b32_e32 v70, v149
	v_mul_f32_e32 v68, 0x3fb8aa3b, v68
	v_exp_f32_e32 v155, v68
	v_mov_b32_e32 v149, v66
	v_mul_f32_e32 v69, 0x3fb8aa3b, v69
	v_exp_f32_e32 v157, v69
	v_pk_add_f32 v[162:163], v[148:149], 0 op_sel_hi:[1,0]
	v_mov_b32_e32 v152, v180
	v_mov_b32_e32 v154, v181
	v_cvt_pk_bf16_f32 v66, v148, v152
	v_pk_add_f32 v[162:163], v[152:153], v[162:163]
	v_mov_b32_e32 v156, v182
	v_mov_b32_e32 v158, v183
	v_pk_add_f32 v[162:163], v[154:155], v[162:163]
	v_cvt_pk_bf16_f32 v67, v154, v156
	v_mul_f32_e32 v71, 0x3fb8aa3b, v72
	v_exp_f32_e32 v71, v71
	v_mul_f32_e32 v72, 0x3fb8aa3b, v73
	v_exp_f32_e32 v148, v72
	v_mul_f32_e32 v72, 0x3fb8aa3b, v74
	v_mov_b32_e32 v160, v184
	v_exp_f32_e32 v74, v72
	v_mul_f32_e32 v72, 0x3fb8aa3b, v75
	v_exp_f32_e32 v75, v72
	v_mul_f32_e32 v72, 0x3fb8aa3b, v76
	v_pk_add_f32 v[162:163], v[156:157], v[162:163]
	v_exp_f32_e32 v156, v72
	v_mul_f32_e32 v72, 0x3fb8aa3b, v77
	v_mov_b32_e32 v77, v148
	v_cvt_pk_bf16_f32 v68, v158, v160
	v_pk_add_f32 v[162:163], v[158:159], v[162:163]
	v_exp_f32_e32 v181, v72
	v_mul_f32_e32 v72, 0x3fb8aa3b, v78
	v_mov_b32_e32 v76, v222
	v_pk_add_f32 v[162:163], v[160:161], v[162:163]
	v_exp_f32_e32 v183, v72
	v_mul_f32_e32 v72, 0x3fb8aa3b, v79
	v_mov_b32_e32 v79, v74
	v_exp_f32_e32 v185, v72
	v_mul_f32_e32 v72, 0x3fb8aa3b, v80
	v_mov_b32_e32 v78, v221
	v_exp_f32_e32 v226, v72
	v_mul_f32_e32 v72, 0x3fb8aa3b, v81
	v_mov_b32_e32 v81, v75
	v_mov_b32_e32 v80, v220
	v_exp_f32_e32 v227, v72
	v_pk_add_f32 v[72:73], v[70:71], v[162:163]
	v_mov_b32_e32 v163, v156
	v_mov_b32_e32 v162, v219
	v_mov_b32_e32 v180, v218
	v_mov_b32_e32 v182, v217
	v_mov_b32_e32 v184, v216
	v_mov_b32_e32 v217, v226
	v_pk_add_f32 v[72:73], v[76:77], v[72:73]
	v_mov_b32_e32 v216, v215
	v_cvt_pk_bf16_f32 v69, v70, v76
	v_pk_add_f32 v[72:73], v[78:79], v[72:73]
	v_pk_add_f32 v[72:73], v[80:81], v[72:73]
	s_waitcnt lgkmcnt(3)
	v_mfma_f32_32x32x16_bf16 v[34:49], v[66:69], v[114:117], v[34:49]
	v_add_f32_e64 v72, v162, v72
	v_add_f32_e64 v73, v163, v73
	v_mov_b32_e32 v215, v227
	v_add_f32_e64 v72, v180, v72
	v_add_f32_e64 v73, v181, v73
	v_pk_add_f32 v[72:73], v[182:183], v[72:73]
	v_cvt_pk_bf16_f32 v74, v182, v184
	v_pk_add_f32 v[72:73], v[184:185], v[72:73]
	s_waitcnt lgkmcnt(1)
	v_mfma_f32_32x32x16_bf16 v[50:65], v[66:69], v[126:129], v[50:65]
	v_cvt_pk_bf16_f32 v66, v149, v153
	v_cvt_pk_bf16_f32 v67, v155, v157
	v_cvt_pk_bf16_f32 v68, v159, v161
	v_cvt_pk_bf16_f32 v69, v71, v77
	v_add_f32_e64 v72, v216, v72
	v_add_f32_e64 v73, v217, v73
	v_pk_add_f32 v[218:219], v[214:215], v[72:73]
	v_cvt_pk_bf16_f32 v72, v78, v80
	v_cvt_pk_bf16_f32 v73, v162, v180
	v_cvt_pk_bf16_f32 v75, v216, v214
	v_mfma_f32_32x32x16_bf16 v[18:33], v[66:69], v[114:117], v[18:33]
	v_cvt_pk_bf16_f32 v70, v79, v81
	v_cvt_pk_bf16_f32 v71, v163, v181
	v_add_f32_e64 v130, v130, v218
	v_add_f32_e64 v131, v131, v219
	v_mfma_f32_32x32x16_bf16 v[2:17], v[66:69], v[126:129], v[2:17]
	v_mfma_f32_32x32x16_bf16 v[34:49], v[72:75], v[118:121], v[34:49]
	s_waitcnt lgkmcnt(0)
	v_mfma_f32_32x32x16_bf16 v[50:65], v[72:75], v[122:125], v[50:65]
	v_cvt_pk_bf16_f32 v72, v183, v185
	v_cvt_pk_bf16_f32 v73, v217, v215
	s_nop 1
	v_mfma_f32_32x32x16_bf16 v[18:33], v[70:73], v[118:121], v[18:33]
	v_mfma_f32_32x32x16_bf16 v[2:17], v[70:73], v[122:125], v[2:17]
	s_cbranch_scc1 .Lattn_nm
	s_branch .LBB0_492
